# up GEMM epilogue: row-stat loads hoisted above K-loop, 8 serialising vmcnt(0) removed
# speedup vs baseline: 1.1868x; 1.1868x over previous
.LBB0_1123:
	s_ashr_i32 s43, s42, 31
	s_lshl_b64 s[34:35], s[42:43], 20
	s_add_u32 s48, s26, s34
	s_addc_u32 s49, s56, s35
	s_and_b64 s[34:35], s[0:1], exec
	s_cselect_b32 s43, s49, s59
	s_cselect_b32 s74, s48, s58
	s_ashr_i32 s37, s36, 31
	s_lshl_b64 s[34:35], s[36:37], 20
	s_add_u32 s50, s57, s34
	s_addc_u32 s51, s60, s35
	s_and_b64 s[34:35], s[0:1], exec
	s_cselect_b32 s37, s51, s19
	s_cselect_b32 s75, s50, s18
	s_add_u32 s76, s18, 0x100
	s_addc_u32 s77, s19, 0
	s_add_u32 s58, s58, 0x80080
	v_mov_b32_e32 v0, 0
	s_addc_u32 s59, s59, 0
	s_mov_b32 s78, -2
	v_mov_b32_e32 v1, v0
	v_mov_b32_e32 v2, v0
	v_mov_b32_e32 v3, v0
	v_mov_b32_e32 v4, v0
	v_mov_b32_e32 v5, v0
	v_mov_b32_e32 v6, v0
	v_mov_b32_e32 v7, v0
	v_mov_b32_e32 v16, v0
	v_mov_b32_e32 v17, v0
	v_mov_b32_e32 v18, v0
	v_mov_b32_e32 v19, v0
	v_mov_b32_e32 v20, v0
	v_mov_b32_e32 v21, v0
	v_mov_b32_e32 v22, v0
	v_mov_b32_e32 v23, v0
	v_mov_b32_e32 v32, v0
	v_mov_b32_e32 v33, v0
	v_mov_b32_e32 v34, v0
	v_mov_b32_e32 v35, v0
	v_mov_b32_e32 v36, v0
	v_mov_b32_e32 v37, v0
	v_mov_b32_e32 v38, v0
	v_mov_b32_e32 v39, v0
	v_mov_b32_e32 v48, v0
	v_mov_b32_e32 v49, v0
	v_mov_b32_e32 v50, v0
	v_mov_b32_e32 v51, v0
	v_mov_b32_e32 v52, v0
	v_mov_b32_e32 v53, v0
	v_mov_b32_e32 v54, v0
	v_mov_b32_e32 v55, v0
	v_mov_b32_e32 v8, v0
	v_mov_b32_e32 v9, v0
	v_mov_b32_e32 v10, v0
	v_mov_b32_e32 v11, v0
	v_mov_b32_e32 v12, v0
	v_mov_b32_e32 v13, v0
	v_mov_b32_e32 v14, v0
	v_mov_b32_e32 v15, v0
	v_mov_b32_e32 v24, v0
	v_mov_b32_e32 v25, v0
	v_mov_b32_e32 v26, v0
	v_mov_b32_e32 v27, v0
	v_mov_b32_e32 v28, v0
	v_mov_b32_e32 v29, v0
	v_mov_b32_e32 v30, v0
	v_mov_b32_e32 v31, v0
	v_mov_b32_e32 v40, v0
	v_mov_b32_e32 v41, v0
	v_mov_b32_e32 v42, v0
	v_mov_b32_e32 v43, v0
	v_mov_b32_e32 v44, v0
	v_mov_b32_e32 v45, v0
	v_mov_b32_e32 v46, v0
	v_mov_b32_e32 v47, v0
	v_mov_b32_e32 v56, v0
	v_mov_b32_e32 v57, v0
	v_mov_b32_e32 v58, v0
	v_mov_b32_e32 v59, v0
	v_mov_b32_e32 v60, v0
	v_mov_b32_e32 v61, v0
	v_mov_b32_e32 v62, v0
	v_mov_b32_e32 v63, v0
	v_mov_b32_e32 v64, v0
	v_mov_b32_e32 v65, v0
	v_mov_b32_e32 v66, v0
	v_mov_b32_e32 v67, v0
	v_mov_b32_e32 v68, v0
	v_mov_b32_e32 v69, v0
	v_mov_b32_e32 v70, v0
	v_mov_b32_e32 v71, v0
	v_mov_b32_e32 v80, v0
	v_mov_b32_e32 v81, v0
	v_mov_b32_e32 v82, v0
	v_mov_b32_e32 v83, v0
	v_mov_b32_e32 v84, v0
	v_mov_b32_e32 v85, v0
	v_mov_b32_e32 v86, v0
	v_mov_b32_e32 v87, v0
	v_mov_b32_e32 v98, v0
	v_mov_b32_e32 v99, v0
	v_mov_b32_e32 v100, v0
	v_mov_b32_e32 v101, v0
	v_mov_b32_e32 v102, v0
	v_mov_b32_e32 v103, v0
	v_mov_b32_e32 v104, v0
	v_mov_b32_e32 v105, v0
	v_mov_b32_e32 v114, v0
	v_mov_b32_e32 v115, v0
	v_mov_b32_e32 v116, v0
	v_mov_b32_e32 v117, v0
	v_mov_b32_e32 v118, v0
	v_mov_b32_e32 v119, v0
	v_mov_b32_e32 v120, v0
	v_mov_b32_e32 v121, v0
	v_mov_b32_e32 v72, v0
	v_mov_b32_e32 v73, v0
	v_mov_b32_e32 v74, v0
	v_mov_b32_e32 v75, v0
	v_mov_b32_e32 v76, v0
	v_mov_b32_e32 v77, v0
	v_mov_b32_e32 v78, v0
	v_mov_b32_e32 v79, v0
	v_mov_b32_e32 v88, v0
	v_mov_b32_e32 v89, v0
	v_mov_b32_e32 v90, v0
	v_mov_b32_e32 v91, v0
	v_mov_b32_e32 v92, v0
	v_mov_b32_e32 v93, v0
	v_mov_b32_e32 v94, v0
	v_mov_b32_e32 v95, v0
	v_mov_b32_e32 v106, v0
	v_mov_b32_e32 v107, v0
	v_mov_b32_e32 v108, v0
	v_mov_b32_e32 v109, v0
	v_mov_b32_e32 v110, v0
	v_mov_b32_e32 v111, v0
	v_mov_b32_e32 v112, v0
	v_mov_b32_e32 v113, v0
	v_mov_b32_e32 v122, v0
	v_mov_b32_e32 v123, v0
	v_mov_b32_e32 v124, v0
	v_mov_b32_e32 v125, v0
	v_mov_b32_e32 v126, v0
	v_mov_b32_e32 v127, v0
	v_mov_b32_e32 v128, v0
	v_mov_b32_e32 v129, v0
	v_lshl_add_u32 v238, s73, 8, v148
	v_ashrrev_i32_e32 v239, 31, v238
	v_lshl_add_u64 v[238:239], v[238:239], 2, s[22:23]
	global_load_dword v230, v[238:239], off
	global_load_dword v231, v[238:239], off offset:64
	global_load_dword v232, v[238:239], off offset:128
	global_load_dword v233, v[238:239], off offset:192
	global_load_dword v234, v[238:239], off offset:512
	global_load_dword v235, v[238:239], off offset:576
	global_load_dword v236, v[238:239], off offset:640
	global_load_dword v237, v[238:239], off offset:704

.LBB0_1127:
	v_lshl_add_u32 v144, s73, 8, v148
	v_lshl_or_b32 v140, s72, 8, v150
	v_ashrrev_i32_e32 v145, 31, v144
	v_ashrrev_i32_e32 v141, 31, v140
	v_lshlrev_b64 v[142:143], 14, v[144:145]
	v_lshl_add_u64 v[142:143], s[14:15], 0, v[142:143]
	v_lshlrev_b64 v[146:147], 1, v[140:141]
	v_lshl_add_u64 v[140:141], v[142:143], 0, v[146:147]
	v_lshl_add_u64 v[142:143], v[144:145], 2, s[22:23]
	s_nop 1
	s_mov_b64 s[18:19], 0x200000
	v_mov_b32_e32 v145, v230
	v_fmamk_f32 v145, v145, 0x3a000000, v194
	v_cmp_gt_f32_e32 vcc, s38, v145
	v_mul_f32_e32 v152, 0x4b800000, v145
	s_nop 0
	v_cndmask_b32_e32 v145, v145, v152, vcc
	v_rsq_f32_e32 v145, v145
	s_nop 0
	v_mul_f32_e32 v152, 0x45800000, v145
	v_cndmask_b32_e32 v152, v145, v152, vcc
	v_pk_mul_f32 v[122:123], v[122:123], v[152:153] op_sel_hi:[1,0]
	v_pk_mul_f32 v[126:127], v[126:127], v[152:153] op_sel_hi:[1,0]
	v_pk_mul_f32 v[124:125], v[124:125], v[152:153] op_sel_hi:[1,0]
	v_max_f32_e32 v122, 0, v122
	v_pk_mul_f32 v[128:129], v[128:129], v[152:153] op_sel_hi:[1,0]
	v_mul_f32_e32 v145, v122, v122
	v_max_f32_e32 v122, 0, v127
	v_max_f32_e32 v123, 0, v123
	v_max_f32_e32 v124, 0, v124
	v_max_f32_e32 v126, 0, v126
	v_mul_f32_e32 v122, v122, v122
	v_mul_f32_e32 v127, v123, v123
	v_max_f32_e32 v123, 0, v128
	v_mul_f32_e32 v128, v124, v124
	v_max_f32_e32 v124, 0, v129
	v_max_f32_e32 v125, 0, v125
	v_pk_mul_f32 v[116:117], v[116:117], v[152:153] op_sel_hi:[1,0]
	v_pk_mul_f32 v[114:115], v[114:115], v[152:153] op_sel_hi:[1,0]
	v_mul_f32_e32 v126, v126, v126
	v_mul_f32_e32 v123, v123, v123
	v_mul_f32_e32 v124, v124, v124
	v_mul_f32_e32 v125, v125, v125
	v_cvt_pk_bf16_f32 v122, v126, v122
	v_pk_mul_f32 v[120:121], v[120:121], v[152:153] op_sel_hi:[1,0]
	v_pk_mul_f32 v[118:119], v[118:119], v[152:153] op_sel_hi:[1,0]
	v_max_f32_e32 v114, 0, v114
	v_max_f32_e32 v115, 0, v115
	v_max_f32_e32 v116, 0, v116
	v_cvt_pk_bf16_f32 v123, v123, v124
	v_cvt_pk_bf16_f32 v124, v145, v127
	v_cvt_pk_bf16_f32 v125, v128, v125
	global_store_dwordx4 v[140:141], v[122:125], off
	v_max_f32_e32 v118, 0, v118
	v_max_f32_e32 v117, 0, v117
	v_mul_f32_e32 v122, v114, v114
	v_max_f32_e32 v114, 0, v119
	v_mul_f32_e32 v119, v115, v115
	v_max_f32_e32 v115, 0, v120
	v_mul_f32_e32 v120, v116, v116
	v_max_f32_e32 v116, 0, v121
	v_mul_f32_e32 v114, v114, v114
	v_mul_f32_e32 v115, v115, v115
	v_mul_f32_e32 v116, v116, v116
	v_mul_f32_e32 v118, v118, v118
	v_mul_f32_e32 v117, v117, v117
	v_cvt_pk_bf16_f32 v114, v118, v114
	v_cvt_pk_bf16_f32 v115, v115, v116
	v_cvt_pk_bf16_f32 v116, v122, v119
	v_cvt_pk_bf16_f32 v117, v120, v117
	global_store_dwordx4 v[140:141], v[114:117], off offset:256
	s_nop 1
	v_or_b32_e32 v116, 16, v144
	v_ashrrev_i32_e32 v117, 31, v116
	v_lshlrev_b64 v[114:115], 14, v[116:117]
	v_lshl_add_u64 v[116:117], v[116:117], 2, s[22:23]
	s_nop 1
	v_lshl_add_u64 v[114:115], s[14:15], 0, v[114:115]
	v_lshl_add_u64 v[114:115], v[114:115], 0, v[146:147]
	v_mov_b32_e32 v116, v231
	v_fmamk_f32 v116, v116, 0x3a000000, v194
	v_cmp_gt_f32_e32 vcc, s38, v116
	v_mul_f32_e32 v117, 0x4b800000, v116
	s_nop 0
	v_cndmask_b32_e32 v116, v116, v117, vcc
	v_rsq_f32_e32 v116, v116
	s_nop 0
	v_mul_f32_e32 v117, 0x45800000, v116
	v_cndmask_b32_e32 v116, v116, v117, vcc
	v_pk_mul_f32 v[106:107], v[106:107], v[116:117] op_sel_hi:[1,0]
	v_pk_mul_f32 v[110:111], v[110:111], v[116:117] op_sel_hi:[1,0]
	v_pk_mul_f32 v[108:109], v[108:109], v[116:117] op_sel_hi:[1,0]
	v_max_f32_e32 v106, 0, v106
	v_pk_mul_f32 v[112:113], v[112:113], v[116:117] op_sel_hi:[1,0]
	v_mul_f32_e32 v117, v106, v106
	v_max_f32_e32 v106, 0, v111
	v_max_f32_e32 v107, 0, v107
	v_max_f32_e32 v108, 0, v108
	v_max_f32_e32 v110, 0, v110
	v_mul_f32_e32 v106, v106, v106
	v_mul_f32_e32 v111, v107, v107
	v_max_f32_e32 v107, 0, v112
	v_mul_f32_e32 v112, v108, v108
	v_max_f32_e32 v108, 0, v113
	v_max_f32_e32 v109, 0, v109
	v_pk_mul_f32 v[100:101], v[100:101], v[116:117] op_sel_hi:[1,0]
	v_pk_mul_f32 v[98:99], v[98:99], v[116:117] op_sel_hi:[1,0]
	v_mul_f32_e32 v110, v110, v110
	v_mul_f32_e32 v107, v107, v107
	v_mul_f32_e32 v108, v108, v108
	v_mul_f32_e32 v109, v109, v109
	v_cvt_pk_bf16_f32 v106, v110, v106
	v_pk_mul_f32 v[104:105], v[104:105], v[116:117] op_sel_hi:[1,0]
	v_pk_mul_f32 v[102:103], v[102:103], v[116:117] op_sel_hi:[1,0]
	v_max_f32_e32 v98, 0, v98
	v_max_f32_e32 v99, 0, v99
	v_max_f32_e32 v100, 0, v100
	v_cvt_pk_bf16_f32 v107, v107, v108
	v_cvt_pk_bf16_f32 v108, v117, v111
	v_cvt_pk_bf16_f32 v109, v112, v109
	global_store_dwordx4 v[114:115], v[106:109], off
	v_max_f32_e32 v102, 0, v102
	v_max_f32_e32 v101, 0, v101
	v_mul_f32_e32 v106, v98, v98
	v_max_f32_e32 v98, 0, v103
	v_mul_f32_e32 v103, v99, v99
	v_max_f32_e32 v99, 0, v104
	v_mul_f32_e32 v104, v100, v100
	v_max_f32_e32 v100, 0, v105
	v_mul_f32_e32 v98, v98, v98
	v_mul_f32_e32 v99, v99, v99
	v_mul_f32_e32 v100, v100, v100
	v_mul_f32_e32 v102, v102, v102
	v_mul_f32_e32 v101, v101, v101
	v_cvt_pk_bf16_f32 v98, v102, v98
	v_cvt_pk_bf16_f32 v99, v99, v100
	v_cvt_pk_bf16_f32 v100, v106, v103
	v_cvt_pk_bf16_f32 v101, v104, v101
	global_store_dwordx4 v[114:115], v[98:101], off offset:256
	s_nop 1
	v_or_b32_e32 v100, 32, v144
	v_ashrrev_i32_e32 v101, 31, v100
	v_lshlrev_b64 v[98:99], 14, v[100:101]
	v_lshl_add_u64 v[100:101], v[100:101], 2, s[22:23]
	s_nop 1
	v_lshl_add_u64 v[98:99], s[14:15], 0, v[98:99]
	v_lshl_add_u64 v[98:99], v[98:99], 0, v[146:147]
	v_mov_b32_e32 v100, v232
	v_fmamk_f32 v100, v100, 0x3a000000, v194
	v_cmp_gt_f32_e32 vcc, s38, v100
	v_mul_f32_e32 v101, 0x4b800000, v100
	s_nop 0
	v_cndmask_b32_e32 v100, v100, v101, vcc
	v_rsq_f32_e32 v100, v100
	s_nop 0
	v_mul_f32_e32 v101, 0x45800000, v100
	v_cndmask_b32_e32 v100, v100, v101, vcc
	v_pk_mul_f32 v[88:89], v[88:89], v[100:101] op_sel_hi:[1,0]
	v_pk_mul_f32 v[92:93], v[92:93], v[100:101] op_sel_hi:[1,0]
	v_pk_mul_f32 v[90:91], v[90:91], v[100:101] op_sel_hi:[1,0]
	v_max_f32_e32 v88, 0, v88
	v_pk_mul_f32 v[94:95], v[94:95], v[100:101] op_sel_hi:[1,0]
	v_mul_f32_e32 v101, v88, v88
	v_max_f32_e32 v88, 0, v93
	v_max_f32_e32 v89, 0, v89
	v_max_f32_e32 v90, 0, v90
	v_max_f32_e32 v92, 0, v92
	v_mul_f32_e32 v88, v88, v88
	v_mul_f32_e32 v93, v89, v89
	v_max_f32_e32 v89, 0, v94
	v_mul_f32_e32 v94, v90, v90
	v_max_f32_e32 v90, 0, v95
	v_max_f32_e32 v91, 0, v91
	v_pk_mul_f32 v[82:83], v[82:83], v[100:101] op_sel_hi:[1,0]
	v_pk_mul_f32 v[80:81], v[80:81], v[100:101] op_sel_hi:[1,0]
	v_mul_f32_e32 v92, v92, v92
	v_mul_f32_e32 v89, v89, v89
	v_mul_f32_e32 v90, v90, v90
	v_mul_f32_e32 v91, v91, v91
	v_cvt_pk_bf16_f32 v88, v92, v88
	v_pk_mul_f32 v[86:87], v[86:87], v[100:101] op_sel_hi:[1,0]
	v_pk_mul_f32 v[84:85], v[84:85], v[100:101] op_sel_hi:[1,0]
	v_max_f32_e32 v80, 0, v80
	v_max_f32_e32 v81, 0, v81
	v_max_f32_e32 v82, 0, v82
	v_cvt_pk_bf16_f32 v89, v89, v90
	v_cvt_pk_bf16_f32 v90, v101, v93
	v_cvt_pk_bf16_f32 v91, v94, v91
	global_store_dwordx4 v[98:99], v[88:91], off
	v_max_f32_e32 v84, 0, v84
	v_max_f32_e32 v83, 0, v83
	v_mul_f32_e32 v88, v80, v80
	v_max_f32_e32 v80, 0, v85
	v_mul_f32_e32 v85, v81, v81
	v_max_f32_e32 v81, 0, v86
	v_mul_f32_e32 v86, v82, v82
	v_max_f32_e32 v82, 0, v87
	v_mul_f32_e32 v80, v80, v80
	v_mul_f32_e32 v81, v81, v81
	v_mul_f32_e32 v82, v82, v82
	v_mul_f32_e32 v84, v84, v84
	v_mul_f32_e32 v83, v83, v83
	v_cvt_pk_bf16_f32 v80, v84, v80
	v_cvt_pk_bf16_f32 v81, v81, v82
	v_cvt_pk_bf16_f32 v82, v88, v85
	v_cvt_pk_bf16_f32 v83, v86, v83
	global_store_dwordx4 v[98:99], v[80:83], off offset:256
	s_nop 1
	v_or_b32_e32 v82, 48, v144
	v_ashrrev_i32_e32 v83, 31, v82
	v_lshlrev_b64 v[80:81], 14, v[82:83]
	v_lshl_add_u64 v[82:83], v[82:83], 2, s[22:23]
	s_nop 1
	v_lshl_add_u64 v[80:81], s[14:15], 0, v[80:81]
	v_lshl_add_u64 v[80:81], v[80:81], 0, v[146:147]
	v_mov_b32_e32 v82, v233
	v_fmamk_f32 v82, v82, 0x3a000000, v194
	v_cmp_gt_f32_e32 vcc, s38, v82
	v_mul_f32_e32 v83, 0x4b800000, v82
	s_nop 0
	v_cndmask_b32_e32 v82, v82, v83, vcc
	v_rsq_f32_e32 v82, v82
	s_nop 0
	v_mul_f32_e32 v83, 0x45800000, v82
	v_cndmask_b32_e32 v82, v82, v83, vcc
	v_pk_mul_f32 v[72:73], v[72:73], v[82:83] op_sel_hi:[1,0]
	v_pk_mul_f32 v[76:77], v[76:77], v[82:83] op_sel_hi:[1,0]
	v_pk_mul_f32 v[74:75], v[74:75], v[82:83] op_sel_hi:[1,0]
	v_max_f32_e32 v72, 0, v72
	v_pk_mul_f32 v[78:79], v[78:79], v[82:83] op_sel_hi:[1,0]
	v_mul_f32_e32 v83, v72, v72
	v_max_f32_e32 v72, 0, v77
	v_max_f32_e32 v73, 0, v73
	v_max_f32_e32 v74, 0, v74
	v_max_f32_e32 v76, 0, v76
	v_mul_f32_e32 v72, v72, v72
	v_mul_f32_e32 v77, v73, v73
	v_max_f32_e32 v73, 0, v78
	v_mul_f32_e32 v78, v74, v74
	v_max_f32_e32 v74, 0, v79
	v_max_f32_e32 v75, 0, v75
	v_pk_mul_f32 v[66:67], v[66:67], v[82:83] op_sel_hi:[1,0]
	v_pk_mul_f32 v[64:65], v[64:65], v[82:83] op_sel_hi:[1,0]
	v_mul_f32_e32 v76, v76, v76
	v_mul_f32_e32 v73, v73, v73
	v_mul_f32_e32 v74, v74, v74
	v_mul_f32_e32 v75, v75, v75
	v_cvt_pk_bf16_f32 v72, v76, v72
	v_pk_mul_f32 v[70:71], v[70:71], v[82:83] op_sel_hi:[1,0]
	v_pk_mul_f32 v[68:69], v[68:69], v[82:83] op_sel_hi:[1,0]
	v_max_f32_e32 v64, 0, v64
	v_max_f32_e32 v65, 0, v65
	v_max_f32_e32 v66, 0, v66
	v_cvt_pk_bf16_f32 v73, v73, v74
	v_cvt_pk_bf16_f32 v74, v83, v77
	v_cvt_pk_bf16_f32 v75, v78, v75
	global_store_dwordx4 v[80:81], v[72:75], off
	v_max_f32_e32 v67, 0, v67
	v_max_f32_e32 v68, 0, v68
	v_mul_f32_e32 v72, v64, v64
	v_max_f32_e32 v64, 0, v69
	v_mul_f32_e32 v69, v65, v65
	v_max_f32_e32 v65, 0, v70
	v_mul_f32_e32 v70, v66, v66
	v_max_f32_e32 v66, 0, v71
	v_mul_f32_e32 v64, v64, v64
	v_mul_f32_e32 v65, v65, v65
	v_mul_f32_e32 v66, v66, v66
	v_mul_f32_e32 v67, v67, v67
	v_mul_f32_e32 v68, v68, v68
	v_cvt_pk_bf16_f32 v64, v68, v64
	v_cvt_pk_bf16_f32 v65, v65, v66
	v_cvt_pk_bf16_f32 v66, v72, v69
	v_cvt_pk_bf16_f32 v67, v70, v67
	global_store_dwordx4 v[80:81], v[64:67], off offset:256
	s_nop 1
	s_nop 0
	v_lshl_add_u64 v[64:65], v[140:141], 0, s[18:19]
	s_mov_b32 s18, 0x200000
	v_mov_b32_e32 v66, v234
	v_fmamk_f32 v66, v66, 0x3a000000, v194
	v_cmp_gt_f32_e32 vcc, s38, v66
	v_mul_f32_e32 v67, 0x4b800000, v66
	s_nop 0
	v_cndmask_b32_e32 v66, v66, v67, vcc
	v_rsq_f32_e32 v66, v66
	s_nop 0
	v_mul_f32_e32 v67, 0x45800000, v66
	v_cndmask_b32_e32 v66, v66, v67, vcc
	v_pk_mul_f32 v[56:57], v[56:57], v[66:67] op_sel_hi:[1,0]
	v_pk_mul_f32 v[60:61], v[60:61], v[66:67] op_sel_hi:[1,0]
	v_pk_mul_f32 v[58:59], v[58:59], v[66:67] op_sel_hi:[1,0]
	v_max_f32_e32 v56, 0, v56
	v_pk_mul_f32 v[62:63], v[62:63], v[66:67] op_sel_hi:[1,0]
	v_max_f32_e32 v60, 0, v60
	v_mul_f32_e32 v67, v56, v56
	v_max_f32_e32 v56, 0, v61
	v_max_f32_e32 v57, 0, v57
	v_max_f32_e32 v58, 0, v58
	v_mul_f32_e32 v60, v60, v60
	v_mul_f32_e32 v56, v56, v56
	v_mul_f32_e32 v61, v57, v57
	v_max_f32_e32 v57, 0, v62
	v_mul_f32_e32 v62, v58, v58
	v_max_f32_e32 v58, 0, v63
	v_mul_f32_e32 v57, v57, v57
	v_max_f32_e32 v59, 0, v59
	v_mul_f32_e32 v58, v58, v58
	v_cvt_pk_bf16_f32 v56, v60, v56
	v_add_co_u32_e32 v60, vcc, s18, v140
	v_pk_mul_f32 v[50:51], v[50:51], v[66:67] op_sel_hi:[1,0]
	v_pk_mul_f32 v[48:49], v[48:49], v[66:67] op_sel_hi:[1,0]
	v_mul_f32_e32 v59, v59, v59
	v_cvt_pk_bf16_f32 v57, v57, v58
	v_cvt_pk_bf16_f32 v58, v67, v61
	v_addc_co_u32_e32 v61, vcc, 0, v141, vcc
	v_pk_mul_f32 v[54:55], v[54:55], v[66:67] op_sel_hi:[1,0]
	v_pk_mul_f32 v[52:53], v[52:53], v[66:67] op_sel_hi:[1,0]
	v_max_f32_e32 v48, 0, v48
	v_max_f32_e32 v49, 0, v49
	v_max_f32_e32 v50, 0, v50
	v_cvt_pk_bf16_f32 v59, v62, v59
	global_store_dwordx4 v[60:61], v[56:59], off
	v_max_f32_e32 v51, 0, v51
	v_max_f32_e32 v52, 0, v52
	v_mul_f32_e32 v56, v48, v48
	v_max_f32_e32 v48, 0, v53
	v_mul_f32_e32 v53, v49, v49
	v_max_f32_e32 v49, 0, v54
	v_mul_f32_e32 v54, v50, v50
	v_max_f32_e32 v50, 0, v55
	v_mul_f32_e32 v48, v48, v48
	v_mul_f32_e32 v49, v49, v49
	v_mul_f32_e32 v50, v50, v50
	v_mul_f32_e32 v51, v51, v51
	v_mul_f32_e32 v52, v52, v52
	v_cvt_pk_bf16_f32 v48, v52, v48
	v_cvt_pk_bf16_f32 v49, v49, v50
	v_cvt_pk_bf16_f32 v50, v56, v53
	v_cvt_pk_bf16_f32 v51, v54, v51
	global_store_dwordx4 v[64:65], v[48:51], off offset:256
	s_nop 1
	s_mov_b64 s[18:19], 0x240000
	v_lshl_add_u64 v[48:49], v[140:141], 0, s[18:19]
	s_mov_b32 s18, 0x240000
	v_mov_b32_e32 v50, v235
	v_fmamk_f32 v50, v50, 0x3a000000, v194
	v_cmp_gt_f32_e32 vcc, s38, v50
	v_mul_f32_e32 v51, 0x4b800000, v50
	s_nop 0
	v_cndmask_b32_e32 v50, v50, v51, vcc
	v_rsq_f32_e32 v50, v50
	s_nop 0
	v_mul_f32_e32 v51, 0x45800000, v50
	v_cndmask_b32_e32 v50, v50, v51, vcc
	v_pk_mul_f32 v[40:41], v[40:41], v[50:51] op_sel_hi:[1,0]
	v_pk_mul_f32 v[44:45], v[44:45], v[50:51] op_sel_hi:[1,0]
	v_pk_mul_f32 v[42:43], v[42:43], v[50:51] op_sel_hi:[1,0]
	v_max_f32_e32 v40, 0, v40
	v_pk_mul_f32 v[46:47], v[46:47], v[50:51] op_sel_hi:[1,0]
	v_max_f32_e32 v44, 0, v44
	v_mul_f32_e32 v51, v40, v40
	v_max_f32_e32 v40, 0, v45
	v_max_f32_e32 v41, 0, v41
	v_max_f32_e32 v42, 0, v42
	v_mul_f32_e32 v44, v44, v44
	v_mul_f32_e32 v40, v40, v40
	v_mul_f32_e32 v45, v41, v41
	v_max_f32_e32 v41, 0, v46
	v_mul_f32_e32 v46, v42, v42
	v_max_f32_e32 v42, 0, v47
	v_mul_f32_e32 v41, v41, v41
	v_max_f32_e32 v43, 0, v43
	v_mul_f32_e32 v42, v42, v42
	v_cvt_pk_bf16_f32 v40, v44, v40
	v_add_co_u32_e32 v44, vcc, s18, v140
	v_pk_mul_f32 v[34:35], v[34:35], v[50:51] op_sel_hi:[1,0]
	v_pk_mul_f32 v[32:33], v[32:33], v[50:51] op_sel_hi:[1,0]
	v_mul_f32_e32 v43, v43, v43
	v_cvt_pk_bf16_f32 v41, v41, v42
	v_cvt_pk_bf16_f32 v42, v51, v45
	v_addc_co_u32_e32 v45, vcc, 0, v141, vcc
	v_pk_mul_f32 v[38:39], v[38:39], v[50:51] op_sel_hi:[1,0]
	v_pk_mul_f32 v[36:37], v[36:37], v[50:51] op_sel_hi:[1,0]
	v_max_f32_e32 v32, 0, v32
	v_max_f32_e32 v33, 0, v33
	v_max_f32_e32 v34, 0, v34
	v_cvt_pk_bf16_f32 v43, v46, v43
	global_store_dwordx4 v[44:45], v[40:43], off
	v_max_f32_e32 v35, 0, v35
	v_max_f32_e32 v36, 0, v36
	v_mul_f32_e32 v40, v32, v32
	v_max_f32_e32 v32, 0, v37
	v_mul_f32_e32 v37, v33, v33
	v_max_f32_e32 v33, 0, v38
	v_mul_f32_e32 v38, v34, v34
	v_max_f32_e32 v34, 0, v39
	v_mul_f32_e32 v32, v32, v32
	v_mul_f32_e32 v33, v33, v33
	v_mul_f32_e32 v34, v34, v34
	v_mul_f32_e32 v35, v35, v35
	v_mul_f32_e32 v36, v36, v36
	v_cvt_pk_bf16_f32 v32, v36, v32
	v_cvt_pk_bf16_f32 v33, v33, v34
	v_cvt_pk_bf16_f32 v34, v40, v37
	v_cvt_pk_bf16_f32 v35, v38, v35
	global_store_dwordx4 v[48:49], v[32:35], off offset:256
	s_nop 1
	s_mov_b64 s[18:19], 0x280000
	v_lshl_add_u64 v[32:33], v[140:141], 0, s[18:19]
	s_mov_b32 s18, 0x280000
	v_mov_b32_e32 v34, v236
	v_fmamk_f32 v34, v34, 0x3a000000, v194
	v_cmp_gt_f32_e32 vcc, s38, v34
	v_mul_f32_e32 v35, 0x4b800000, v34
	s_nop 0
	v_cndmask_b32_e32 v34, v34, v35, vcc
	v_rsq_f32_e32 v34, v34
	s_nop 0
	v_mul_f32_e32 v35, 0x45800000, v34
	v_cndmask_b32_e32 v34, v34, v35, vcc
	v_pk_mul_f32 v[24:25], v[24:25], v[34:35] op_sel_hi:[1,0]
	v_pk_mul_f32 v[28:29], v[28:29], v[34:35] op_sel_hi:[1,0]
	v_pk_mul_f32 v[26:27], v[26:27], v[34:35] op_sel_hi:[1,0]
	v_max_f32_e32 v24, 0, v24
	v_pk_mul_f32 v[30:31], v[30:31], v[34:35] op_sel_hi:[1,0]
	v_max_f32_e32 v28, 0, v28
	v_mul_f32_e32 v35, v24, v24
	v_max_f32_e32 v24, 0, v29
	v_max_f32_e32 v25, 0, v25
	v_max_f32_e32 v26, 0, v26
	v_mul_f32_e32 v28, v28, v28
	v_mul_f32_e32 v24, v24, v24
	v_mul_f32_e32 v29, v25, v25
	v_max_f32_e32 v25, 0, v30
	v_mul_f32_e32 v30, v26, v26
	v_max_f32_e32 v26, 0, v31
	v_mul_f32_e32 v25, v25, v25
	v_max_f32_e32 v27, 0, v27
	v_mul_f32_e32 v26, v26, v26
	v_cvt_pk_bf16_f32 v24, v28, v24
	v_add_co_u32_e32 v28, vcc, s18, v140
	v_pk_mul_f32 v[18:19], v[18:19], v[34:35] op_sel_hi:[1,0]
	v_pk_mul_f32 v[16:17], v[16:17], v[34:35] op_sel_hi:[1,0]
	v_mul_f32_e32 v27, v27, v27
	v_cvt_pk_bf16_f32 v25, v25, v26
	v_cvt_pk_bf16_f32 v26, v35, v29
	v_addc_co_u32_e32 v29, vcc, 0, v141, vcc
	v_pk_mul_f32 v[22:23], v[22:23], v[34:35] op_sel_hi:[1,0]
	v_pk_mul_f32 v[20:21], v[20:21], v[34:35] op_sel_hi:[1,0]
	v_max_f32_e32 v16, 0, v16
	v_max_f32_e32 v17, 0, v17
	v_max_f32_e32 v18, 0, v18
	v_cvt_pk_bf16_f32 v27, v30, v27
	global_store_dwordx4 v[28:29], v[24:27], off
	v_max_f32_e32 v19, 0, v19
	v_max_f32_e32 v20, 0, v20
	v_mul_f32_e32 v24, v16, v16
	v_max_f32_e32 v16, 0, v21
	v_mul_f32_e32 v21, v17, v17
	v_max_f32_e32 v17, 0, v22
	v_mul_f32_e32 v22, v18, v18
	v_max_f32_e32 v18, 0, v23
	v_mul_f32_e32 v16, v16, v16
	v_mul_f32_e32 v17, v17, v17
	v_mul_f32_e32 v18, v18, v18
	v_mul_f32_e32 v19, v19, v19
	v_mul_f32_e32 v20, v20, v20
	v_cvt_pk_bf16_f32 v16, v20, v16
	v_cvt_pk_bf16_f32 v17, v17, v18
	v_cvt_pk_bf16_f32 v18, v24, v21
	v_cvt_pk_bf16_f32 v19, v22, v19
	global_store_dwordx4 v[32:33], v[16:19], off offset:256
	s_nop 1
	s_mov_b64 s[18:19], 0x2c0000
	v_lshl_add_u64 v[16:17], v[140:141], 0, s[18:19]
	s_mov_b32 s18, 0x2c0000
	v_mov_b32_e32 v18, v237
	v_fmamk_f32 v18, v18, 0x3a000000, v194
	v_cmp_gt_f32_e32 vcc, s38, v18
	v_mul_f32_e32 v19, 0x4b800000, v18
	s_nop 0
	v_cndmask_b32_e32 v18, v18, v19, vcc
	v_rsq_f32_e32 v18, v18
	s_nop 0
	v_mul_f32_e32 v19, 0x45800000, v18
	v_cndmask_b32_e32 v18, v18, v19, vcc
	v_pk_mul_f32 v[8:9], v[8:9], v[18:19] op_sel_hi:[1,0]
	v_pk_mul_f32 v[12:13], v[12:13], v[18:19] op_sel_hi:[1,0]
	v_pk_mul_f32 v[10:11], v[10:11], v[18:19] op_sel_hi:[1,0]
	v_max_f32_e32 v8, 0, v8
	v_pk_mul_f32 v[14:15], v[14:15], v[18:19] op_sel_hi:[1,0]
	v_max_f32_e32 v12, 0, v12
	v_mul_f32_e32 v19, v8, v8
	v_max_f32_e32 v8, 0, v13
	v_max_f32_e32 v9, 0, v9
	v_max_f32_e32 v10, 0, v10
	v_mul_f32_e32 v12, v12, v12
	v_mul_f32_e32 v8, v8, v8
	v_mul_f32_e32 v13, v9, v9
	v_max_f32_e32 v9, 0, v14
	v_mul_f32_e32 v14, v10, v10
	v_max_f32_e32 v10, 0, v15
	v_mul_f32_e32 v9, v9, v9
	v_max_f32_e32 v11, 0, v11
	v_mul_f32_e32 v10, v10, v10
	v_cvt_pk_bf16_f32 v8, v12, v8
	v_add_co_u32_e32 v12, vcc, s18, v140
	v_pk_mul_f32 v[2:3], v[2:3], v[18:19] op_sel_hi:[1,0]
	v_pk_mul_f32 v[0:1], v[0:1], v[18:19] op_sel_hi:[1,0]
	v_mul_f32_e32 v11, v11, v11
	v_cvt_pk_bf16_f32 v9, v9, v10
	v_cvt_pk_bf16_f32 v10, v19, v13
	v_addc_co_u32_e32 v13, vcc, 0, v141, vcc
	v_pk_mul_f32 v[6:7], v[6:7], v[18:19] op_sel_hi:[1,0]
	v_pk_mul_f32 v[4:5], v[4:5], v[18:19] op_sel_hi:[1,0]
	v_max_f32_e32 v0, 0, v0
	v_max_f32_e32 v1, 0, v1
	v_max_f32_e32 v2, 0, v2
	v_cvt_pk_bf16_f32 v11, v14, v11
	global_store_dwordx4 v[12:13], v[8:11], off
	v_max_f32_e32 v3, 0, v3
	v_max_f32_e32 v4, 0, v4
	v_mul_f32_e32 v8, v0, v0
	v_max_f32_e32 v0, 0, v5
	v_mul_f32_e32 v5, v1, v1
	v_max_f32_e32 v1, 0, v6
	v_mul_f32_e32 v6, v2, v2
	v_max_f32_e32 v2, 0, v7
	v_mul_f32_e32 v0, v0, v0
	v_mul_f32_e32 v1, v1, v1
	v_mul_f32_e32 v2, v2, v2
	v_mul_f32_e32 v3, v3, v3
	s_mov_b64 s[18:19], -1
	s_andn2_b64 vcc, exec, s[0:1]
	v_mul_f32_e32 v4, v4, v4
	v_cvt_pk_bf16_f32 v0, v4, v0
	v_cvt_pk_bf16_f32 v1, v1, v2
	v_cvt_pk_bf16_f32 v2, v8, v5
	v_cvt_pk_bf16_f32 v3, v6, v3
	global_store_dwordx4 v[16:17], v[0:3], off offset:256
	s_cbranch_vccnz .LBB0_1116
	s_andn2_b64 vcc, exec, s[12:13]
	s_cbranch_vccnz .LBB0_1115
	s_barrier
	s_branch .LBB0_1115
